# non-leader workgroups poll the global TOPGEN word instead of their XCD generation word in all 13 grid-barrier copies (skips the leader-to-local release hop)
# speedup vs baseline: 1.0079x; 1.0079x over previous
; __device__ __forceinline__ unsigned xb_ld(unsigned* p)              { return __hip_atomic_load(p, __ATOMIC_RELAXED, __HIP_MEMORY_SCOPE_AGENT); }
; __device__ __forceinline__ unsigned xb_add(unsigned* p, unsigned v) { return __hip_atomic_fetch_add(p, v, __ATOMIC_RELAXED, __HIP_MEMORY_SCOPE_AGENT); }
; #define XB_SPIN(cond, bar) do { unsigned _sp = 0; while (cond) { __builtin_amdgcn_s_sleep(1); \
;     if ((++_sp & 255u) == 0u) { if (xb_ld(&(bar)[XB_TMO])) break; if (_sp > XB_SPIN_CAP) { atomicAdd(&(bar)[XB_TMO], 1u); break; } } } } while (0)
; __device__ __forceinline__ void xcd_barrier(const XcdBarrier& b) {
;     ...
;         unsigned nloc = b.st[0], nx = b.st[1];
;         if (nloc == 0u) { xcd_barrier_complete(bar, b.x, nloc, nx); b.st[0] = nloc; b.st[1] = nx; }
;         const unsigned old = xb_add(&bar[XB_XSUB(b.x)], 1u);
;         const unsigned gen = old / nloc;
;         if (old + 1u == (gen + 1u) * nloc) {
;             __builtin_amdgcn_fence(__ATOMIC_RELEASE, "agent");
;             asm volatile("s_waitcnt vmcnt(0)" ::: "memory");
;             const unsigned og = xb_add(&bar[XB_TOP], 1u);
;             const unsigned tg = og / nx;
;             if (og + 1u == (tg + 1u) * nx) xb_add(&bar[XB_TOPGEN], 1u);
;             else XB_SPIN(xb_ld(&bar[XB_TOPGEN]) == tg, bar);
;             __builtin_amdgcn_fence(__ATOMIC_ACQUIRE, "agent");
;             xb_add(&bar[XB_XGEN(b.x)], 1u);
;             asm volatile("s_waitcnt vmcnt(0)" ::: "memory");
;         } else {
;             XB_SPIN(xb_ld(&bar[XB_XGEN(b.x)]) == gen, bar);
.LBB0_131:
	s_or_b64 exec, exec, s[12:13]
	v_cvt_f32_u32_e32 v5, v3
	s_waitcnt vmcnt(0)
	v_readfirstlane_b32 s2, v4
	v_sub_u32_e32 v4, 0, v3
	v_rcp_iflag_f32_e32 v5, v5
	v_add_u32_e32 v6, s2, v2
	v_mul_f32_e32 v5, 0x4f7ffffe, v5
	v_cvt_u32_f32_e32 v5, v5
	v_mul_lo_u32 v2, v4, v5
	v_mul_hi_u32 v2, v5, v2
	v_add_u32_e32 v2, v5, v2
	v_mul_hi_u32 v2, v6, v2
	v_mul_lo_u32 v4, v2, v3
	v_sub_u32_e32 v4, v6, v4
	v_add_u32_e32 v5, 1, v2
	v_cmp_ge_u32_e32 vcc, v4, v3
	s_nop 1
	v_cndmask_b32_e32 v2, v2, v5, vcc
	v_sub_u32_e32 v5, v4, v3
	v_cndmask_b32_e32 v4, v4, v5, vcc
	v_add_u32_e32 v5, 1, v2
	v_cmp_ge_u32_e32 vcc, v4, v3
	v_add_u32_e32 v4, 1, v6
	s_nop 0
	v_cndmask_b32_e32 v2, v2, v5, vcc
	v_mul_lo_u32 v5, v3, v2
	v_add_u32_e32 v3, v5, v3
	v_cmp_ne_u32_e32 vcc, v4, v3
	s_and_saveexec_b64 s[2:3], vcc
	s_xor_b64 s[10:11], exec, s[2:3]
	s_cbranch_execz .LBB0_145
	s_waitcnt lgkmcnt(0)
	v_mov_b32_e32 v1, 0x7500
	global_load_dword v1, v1, s[6:7] sc1
	s_add_u32 s16, s6, 0x7500
	s_addc_u32 s17, s7, 0
	s_waitcnt vmcnt(0)
	v_cmp_eq_u32_e32 vcc, v1, v2
	s_and_saveexec_b64 s[12:13], vcc
	s_cbranch_execz .LBB0_144
	s_add_u32 s14, s6, 0x4200
	s_addc_u32 s15, s7, 0
	s_mov_b32 s2, 1
	s_mov_b64 s[18:19], 0
	v_mov_b32_e32 v1, 0
	s_branch .LBB0_135

; __device__ __forceinline__ unsigned xb_ld(unsigned* p)              { return __hip_atomic_load(p, __ATOMIC_RELAXED, __HIP_MEMORY_SCOPE_AGENT); }
; __device__ __forceinline__ unsigned xb_add(unsigned* p, unsigned v) { return __hip_atomic_fetch_add(p, v, __ATOMIC_RELAXED, __HIP_MEMORY_SCOPE_AGENT); }
; #define XB_SPIN(cond, bar) do { unsigned _sp = 0; while (cond) { __builtin_amdgcn_s_sleep(1); \
;     if ((++_sp & 255u) == 0u) { if (xb_ld(&(bar)[XB_TMO])) break; if (_sp > XB_SPIN_CAP) { atomicAdd(&(bar)[XB_TMO], 1u); break; } } } } while (0)
; __device__ __forceinline__ void xcd_barrier(const XcdBarrier& b) {
;     ...
;         unsigned nloc = b.st[0], nx = b.st[1];
;         if (nloc == 0u) { xcd_barrier_complete(bar, b.x, nloc, nx); b.st[0] = nloc; b.st[1] = nx; }
;         const unsigned old = xb_add(&bar[XB_XSUB(b.x)], 1u);
;         const unsigned gen = old / nloc;
;         if (old + 1u == (gen + 1u) * nloc) {
;             __builtin_amdgcn_fence(__ATOMIC_RELEASE, "agent");
;             asm volatile("s_waitcnt vmcnt(0)" ::: "memory");
;             const unsigned og = xb_add(&bar[XB_TOP], 1u);
;             const unsigned tg = og / nx;
;             if (og + 1u == (tg + 1u) * nx) xb_add(&bar[XB_TOPGEN], 1u);
;             else XB_SPIN(xb_ld(&bar[XB_TOPGEN]) == tg, bar);
;             __builtin_amdgcn_fence(__ATOMIC_ACQUIRE, "agent");
;             xb_add(&bar[XB_XGEN(b.x)], 1u);
;             asm volatile("s_waitcnt vmcnt(0)" ::: "memory");
;         } else {
;             XB_SPIN(xb_ld(&bar[XB_XGEN(b.x)]) == gen, bar);
.LBB0_239:
	s_or_b64 exec, exec, s[10:11]
	v_cvt_f32_u32_e32 v5, v3
	s_waitcnt vmcnt(0)
	v_readfirstlane_b32 s8, v4
	v_sub_u32_e32 v4, 0, v3
	v_rcp_iflag_f32_e32 v5, v5
	v_add_u32_e32 v6, s8, v1
	v_mul_f32_e32 v5, 0x4f7ffffe, v5
	v_cvt_u32_f32_e32 v5, v5
	v_mul_lo_u32 v1, v4, v5
	v_mul_hi_u32 v1, v5, v1
	v_add_u32_e32 v1, v5, v1
	v_mul_hi_u32 v1, v6, v1
	v_mul_lo_u32 v4, v1, v3
	v_sub_u32_e32 v4, v6, v4
	v_add_u32_e32 v5, 1, v1
	v_cmp_ge_u32_e32 vcc, v4, v3
	s_nop 1
	v_cndmask_b32_e32 v1, v1, v5, vcc
	v_sub_u32_e32 v5, v4, v3
	v_cndmask_b32_e32 v4, v4, v5, vcc
	v_add_u32_e32 v5, 1, v1
	v_cmp_ge_u32_e32 vcc, v4, v3
	v_add_u32_e32 v4, 1, v6
	s_nop 0
	v_cndmask_b32_e32 v1, v1, v5, vcc
	v_mul_lo_u32 v5, v3, v1
	v_add_u32_e32 v3, v5, v3
	v_cmp_ne_u32_e32 vcc, v4, v3
	s_and_saveexec_b64 s[8:9], vcc
	s_xor_b64 s[8:9], exec, s[8:9]
	s_cbranch_execz .LBB0_253
	s_waitcnt lgkmcnt(0)
	v_mov_b32_e32 v2, 0x7500
	global_load_dword v2, v2, s[4:5] sc1
	s_add_u32 s16, s4, 0x7500
	s_addc_u32 s17, s5, 0
	s_waitcnt vmcnt(0)
	v_cmp_eq_u32_e32 vcc, v2, v1
	s_and_saveexec_b64 s[10:11], vcc
	s_cbranch_execz .LBB0_252
	s_add_u32 s12, s4, 0x4200
	s_addc_u32 s13, s5, 0
	s_mov_b32 s28, 1
	s_mov_b64 s[18:19], 0
	s_branch .LBB0_243

; __device__ __forceinline__ unsigned xb_ld(unsigned* p)              { return __hip_atomic_load(p, __ATOMIC_RELAXED, __HIP_MEMORY_SCOPE_AGENT); }
; __device__ __forceinline__ unsigned xb_add(unsigned* p, unsigned v) { return __hip_atomic_fetch_add(p, v, __ATOMIC_RELAXED, __HIP_MEMORY_SCOPE_AGENT); }
; #define XB_SPIN(cond, bar) do { unsigned _sp = 0; while (cond) { __builtin_amdgcn_s_sleep(1); \
;     if ((++_sp & 255u) == 0u) { if (xb_ld(&(bar)[XB_TMO])) break; if (_sp > XB_SPIN_CAP) { atomicAdd(&(bar)[XB_TMO], 1u); break; } } } } while (0)
; __device__ __forceinline__ void xcd_barrier(const XcdBarrier& b) {
;     ...
;         unsigned nloc = b.st[0], nx = b.st[1];
;         if (nloc == 0u) { xcd_barrier_complete(bar, b.x, nloc, nx); b.st[0] = nloc; b.st[1] = nx; }
;         const unsigned old = xb_add(&bar[XB_XSUB(b.x)], 1u);
;         const unsigned gen = old / nloc;
;         if (old + 1u == (gen + 1u) * nloc) {
;             __builtin_amdgcn_fence(__ATOMIC_RELEASE, "agent");
;             asm volatile("s_waitcnt vmcnt(0)" ::: "memory");
;             const unsigned og = xb_add(&bar[XB_TOP], 1u);
;             const unsigned tg = og / nx;
;             if (og + 1u == (tg + 1u) * nx) xb_add(&bar[XB_TOPGEN], 1u);
;             else XB_SPIN(xb_ld(&bar[XB_TOPGEN]) == tg, bar);
;             __builtin_amdgcn_fence(__ATOMIC_ACQUIRE, "agent");
;             xb_add(&bar[XB_XGEN(b.x)], 1u);
;             asm volatile("s_waitcnt vmcnt(0)" ::: "memory");
;         } else {
;             XB_SPIN(xb_ld(&bar[XB_XGEN(b.x)]) == gen, bar);
.LBB0_534:
	s_or_b64 exec, exec, s[10:11]
	v_cvt_f32_u32_e32 v5, v3
	s_waitcnt vmcnt(0)
	v_readfirstlane_b32 s8, v4
	v_sub_u32_e32 v4, 0, v3
	v_rcp_iflag_f32_e32 v5, v5
	v_add_u32_e32 v6, s8, v1
	v_mul_f32_e32 v5, 0x4f7ffffe, v5
	v_cvt_u32_f32_e32 v5, v5
	v_mul_lo_u32 v1, v4, v5
	v_mul_hi_u32 v1, v5, v1
	v_add_u32_e32 v1, v5, v1
	v_mul_hi_u32 v1, v6, v1
	v_mul_lo_u32 v4, v1, v3
	v_sub_u32_e32 v4, v6, v4
	v_add_u32_e32 v5, 1, v1
	v_cmp_ge_u32_e32 vcc, v4, v3
	s_nop 1
	v_cndmask_b32_e32 v1, v1, v5, vcc
	v_sub_u32_e32 v5, v4, v3
	v_cndmask_b32_e32 v4, v4, v5, vcc
	v_add_u32_e32 v5, 1, v1
	v_cmp_ge_u32_e32 vcc, v4, v3
	v_add_u32_e32 v4, 1, v6
	s_nop 0
	v_cndmask_b32_e32 v1, v1, v5, vcc
	v_mul_lo_u32 v5, v3, v1
	v_add_u32_e32 v3, v5, v3
	v_cmp_ne_u32_e32 vcc, v4, v3
	s_and_saveexec_b64 s[8:9], vcc
	s_xor_b64 s[8:9], exec, s[8:9]
	s_cbranch_execz .LBB0_548
	s_waitcnt lgkmcnt(0)
	v_mov_b32_e32 v2, 0x7500
	global_load_dword v2, v2, s[4:5] sc1
	s_add_u32 s14, s4, 0x7500
	s_addc_u32 s15, s5, 0
	s_waitcnt vmcnt(0)
	v_cmp_eq_u32_e32 vcc, v2, v1
	s_and_saveexec_b64 s[10:11], vcc
	s_cbranch_execz .LBB0_547
	s_add_u32 s12, s4, 0x4200
	s_addc_u32 s13, s5, 0
	s_mov_b32 s26, 1
	s_mov_b64 s[16:17], 0
	s_branch .LBB0_538

; __device__ __forceinline__ unsigned xb_ld(unsigned* p)              { return __hip_atomic_load(p, __ATOMIC_RELAXED, __HIP_MEMORY_SCOPE_AGENT); }
; __device__ __forceinline__ unsigned xb_add(unsigned* p, unsigned v) { return __hip_atomic_fetch_add(p, v, __ATOMIC_RELAXED, __HIP_MEMORY_SCOPE_AGENT); }
; #define XB_SPIN(cond, bar) do { unsigned _sp = 0; while (cond) { __builtin_amdgcn_s_sleep(1); \
;     if ((++_sp & 255u) == 0u) { if (xb_ld(&(bar)[XB_TMO])) break; if (_sp > XB_SPIN_CAP) { atomicAdd(&(bar)[XB_TMO], 1u); break; } } } } while (0)
; __device__ __forceinline__ void xcd_barrier(const XcdBarrier& b) {
;     ...
;         unsigned nloc = b.st[0], nx = b.st[1];
;         if (nloc == 0u) { xcd_barrier_complete(bar, b.x, nloc, nx); b.st[0] = nloc; b.st[1] = nx; }
;         const unsigned old = xb_add(&bar[XB_XSUB(b.x)], 1u);
;         const unsigned gen = old / nloc;
;         if (old + 1u == (gen + 1u) * nloc) {
;             __builtin_amdgcn_fence(__ATOMIC_RELEASE, "agent");
;             asm volatile("s_waitcnt vmcnt(0)" ::: "memory");
;             const unsigned og = xb_add(&bar[XB_TOP], 1u);
;             const unsigned tg = og / nx;
;             if (og + 1u == (tg + 1u) * nx) xb_add(&bar[XB_TOPGEN], 1u);
;             else XB_SPIN(xb_ld(&bar[XB_TOPGEN]) == tg, bar);
;             __builtin_amdgcn_fence(__ATOMIC_ACQUIRE, "agent");
;             xb_add(&bar[XB_XGEN(b.x)], 1u);
;             asm volatile("s_waitcnt vmcnt(0)" ::: "memory");
;         } else {
;             XB_SPIN(xb_ld(&bar[XB_XGEN(b.x)]) == gen, bar);
.LBB0_1274:
	s_or_b64 exec, exec, s[12:13]
	v_cvt_f32_u32_e32 v5, v3
	s_waitcnt vmcnt(0)
	v_readfirstlane_b32 s10, v4
	v_sub_u32_e32 v4, 0, v3
	v_rcp_iflag_f32_e32 v5, v5
	v_add_u32_e32 v6, s10, v1
	v_mul_f32_e32 v5, 0x4f7ffffe, v5
	v_cvt_u32_f32_e32 v5, v5
	v_mul_lo_u32 v1, v4, v5
	v_mul_hi_u32 v1, v5, v1
	v_add_u32_e32 v1, v5, v1
	v_mul_hi_u32 v1, v6, v1
	v_mul_lo_u32 v4, v1, v3
	v_sub_u32_e32 v4, v6, v4
	v_add_u32_e32 v5, 1, v1
	v_cmp_ge_u32_e32 vcc, v4, v3
	s_nop 1
	v_cndmask_b32_e32 v1, v1, v5, vcc
	v_sub_u32_e32 v5, v4, v3
	v_cndmask_b32_e32 v4, v4, v5, vcc
	v_add_u32_e32 v5, 1, v1
	v_cmp_ge_u32_e32 vcc, v4, v3
	v_add_u32_e32 v4, 1, v6
	s_nop 0
	v_cndmask_b32_e32 v1, v1, v5, vcc
	v_mul_lo_u32 v5, v3, v1
	v_add_u32_e32 v3, v5, v3
	v_cmp_ne_u32_e32 vcc, v4, v3
	s_and_saveexec_b64 s[10:11], vcc
	s_xor_b64 s[10:11], exec, s[10:11]
	s_cbranch_execz .LBB0_1288
	s_waitcnt lgkmcnt(0)
	v_mov_b32_e32 v2, 0x7500
	global_load_dword v2, v2, s[4:5] sc1
	s_add_u32 s16, s4, 0x7500
	s_addc_u32 s17, s5, 0
	s_waitcnt vmcnt(0)
	v_cmp_eq_u32_e32 vcc, v2, v1
	s_and_saveexec_b64 s[12:13], vcc
	s_cbranch_execz .LBB0_1287
	s_add_u32 s14, s4, 0x4200
	s_addc_u32 s15, s5, 0
	s_mov_b32 s28, 1
	s_mov_b64 s[18:19], 0
	s_branch .LBB0_1278
